# v40 + attention v_pk_fma_f32 split into scalar v_fma_f32 pairs (120 sites), padded +2048B
# baseline (speedup 1.0000x reference)
; #define LAS __attribute__((address_space(3)))
; template <int MODE> ...
;     ...
;     {
;         const LAS unsigned char* kb = lds + AL_KT + fr * KT_PITCH + fq * 16;
;     ...
;         bf16x8 kr[4]; kr[0] = KFRAG(0); kr[1] = KFRAG(1); kr[2] = KFRAG(2);
; #pragma unroll
;         for (int i = 0; i < 16; ++i) {
;             if (i + 3 < 16) kr[(i + 3) & 3] = KFRAG(i + 3);
;             __builtin_amdgcn_sched_barrier(0);
;             s[0][i & 3] = __builtin_amdgcn_mfma_f32_16x16x32_bf16(kr[i & 3], qf[0][i >> 2], s[0][i & 3], 0, 0, 0);
;             s[1][i & 3] = __builtin_amdgcn_mfma_f32_16x16x32_bf16(kr[i & 3], qf[1][i >> 2], s[1][i & 3], 0, 0, 0);
;             __builtin_amdgcn_sched_barrier(0);
;         }
;     ...
;     }
;     const float sk = slope2 * (float)KS;
;     float alpha[2] = {1.f, 1.f};
; #pragma unroll
;     for (int ci = 0; ci < 2; ++ci) {
;         const int base = tpos[ci] - kp0 - KS * (fq * 4);
;         const float bb = -slope2 * (float)base;
;         float mx = NEGB;
; #pragma unroll
;         for (int k4 = 0; k4 < 4; ++k4)
; #pragma unroll
;             for (int j = 0; j < 4; ++j) {
;                 s[ci][k4][j] = __builtin_fmaf(s[ci][k4][j], QSCALE2, __builtin_fmaf(sk, (float)(k4 * 16 + j), bb)); }
;         if (MASK) {
; #pragma unroll
;             for (int k4 = 0; k4 < 4; ++k4)
; #pragma unroll
;                 for (int j = 0; j < 4; ++j) { const int c = KS * (k4 * 16 + j); bool ok = c <= base; if (MODE == 3) ok = ok && (base - c < 512); s[ci][k4][j] = ok ? s[ci][k4][j] : 2.0f * NEGB; } }
.LBB0_3784:
	v_add3_u32 v96, s2, v210, v136
	ds_read_b128 v[52:55], v96 offset:8704
	ds_read_b128 v[56:59], v96 offset:13056
	ds_read_b128 v[60:63], v96 offset:4352
	ds_read_b128 v[64:67], v96
	s_cmp_gt_i32 s10, s16
	s_cselect_b64 s[2:3], -1, 0
	s_cmp_le_i32 s10, s16
	s_waitcnt lgkmcnt(0)
	v_mfma_f32_16x16x32_bf16 v[80:83], v[64:67], v[4:7], 0
	v_mfma_f32_16x16x32_bf16 v[64:67], v[64:67], v[20:23], 0
	ds_read_b128 v[84:87], v96 offset:64
	v_mfma_f32_16x16x32_bf16 v[88:91], v[60:63], v[4:7], 0
	v_mfma_f32_16x16x32_bf16 v[60:63], v[60:63], v[20:23], 0
	ds_read_b128 v[92:95], v96 offset:4416
	v_mfma_f32_16x16x32_bf16 v[106:109], v[52:55], v[4:7], 0
	v_mfma_f32_16x16x32_bf16 v[52:55], v[52:55], v[20:23], 0
	ds_read_b128 v[110:113], v96 offset:8768
	v_mfma_f32_16x16x32_bf16 v[118:121], v[56:59], v[4:7], 0
	v_mfma_f32_16x16x32_bf16 v[56:59], v[56:59], v[20:23], 0
	ds_read_b128 v[122:125], v96 offset:13120
	s_waitcnt lgkmcnt(3)
	v_mfma_f32_16x16x32_bf16 v[80:83], v[84:87], v[8:11], v[80:83]
	v_mfma_f32_16x16x32_bf16 v[64:67], v[84:87], v[24:27], v[64:67]
	ds_read_b128 v[84:87], v96 offset:128
	s_waitcnt lgkmcnt(3)
	v_mfma_f32_16x16x32_bf16 v[88:91], v[92:95], v[8:11], v[88:91]
	v_mfma_f32_16x16x32_bf16 v[60:63], v[92:95], v[24:27], v[60:63]
	ds_read_b128 v[92:95], v96 offset:4480
	s_waitcnt lgkmcnt(3)
	v_mfma_f32_16x16x32_bf16 v[52:55], v[110:113], v[24:27], v[52:55]
	v_mfma_f32_16x16x32_bf16 v[106:109], v[110:113], v[8:11], v[106:109]
	ds_read_b128 v[110:113], v96 offset:8832
	s_waitcnt lgkmcnt(3)
	v_mfma_f32_16x16x32_bf16 v[56:59], v[122:125], v[24:27], v[56:59]
	v_mfma_f32_16x16x32_bf16 v[118:121], v[122:125], v[8:11], v[118:121]
	ds_read_b128 v[122:125], v96 offset:13184
	s_waitcnt lgkmcnt(3)
	v_mfma_f32_16x16x32_bf16 v[80:83], v[84:87], v[12:15], v[80:83]
	v_mfma_f32_16x16x32_bf16 v[64:67], v[84:87], v[28:31], v[64:67]
	ds_read_b128 v[84:87], v96 offset:192
	s_waitcnt lgkmcnt(3)
	v_mfma_f32_16x16x32_bf16 v[88:91], v[92:95], v[12:15], v[88:91]
	v_mfma_f32_16x16x32_bf16 v[60:63], v[92:95], v[28:31], v[60:63]
	ds_read_b128 v[92:95], v96 offset:4544
	s_waitcnt lgkmcnt(3)
	v_mfma_f32_16x16x32_bf16 v[52:55], v[110:113], v[28:31], v[52:55]
	v_mfma_f32_16x16x32_bf16 v[106:109], v[110:113], v[12:15], v[106:109]
	ds_read_b128 v[110:113], v96 offset:8896
	s_waitcnt lgkmcnt(3)
	v_mfma_f32_16x16x32_bf16 v[118:121], v[122:125], v[12:15], v[118:121]
	v_mfma_f32_16x16x32_bf16 v[122:125], v[122:125], v[28:31], v[56:59]
	ds_read_b128 v[126:129], v96 offset:13248
	s_waitcnt lgkmcnt(3)
	v_mfma_f32_16x16x32_bf16 v[80:83], v[84:87], v[16:19], v[80:83]
	v_mfma_f32_16x16x32_bf16 v[64:67], v[84:87], v[32:35], v[64:67]
	s_waitcnt lgkmcnt(2)
	v_mfma_f32_16x16x32_bf16 v[86:89], v[92:95], v[16:19], v[88:91]
	v_mfma_f32_16x16x32_bf16 v[60:63], v[92:95], v[32:35], v[60:63]
	s_waitcnt lgkmcnt(1)
	v_mfma_f32_16x16x32_bf16 v[90:93], v[110:113], v[16:19], v[106:109]
	v_mfma_f32_16x16x32_bf16 v[56:59], v[110:113], v[32:35], v[52:55]
	s_waitcnt lgkmcnt(0)
	v_mfma_f32_16x16x32_bf16 v[52:55], v[126:129], v[32:35], v[122:125]
	v_mfma_f32_16x16x32_bf16 v[106:109], v[126:129], v[16:19], v[118:121]
	v_add_u32_e32 v96, -4, v102
	v_cvt_f32_i32_e32 v85, v96
	s_mov_b32 s12, 2.0
	s_mov_b32 s14, 0x3e0293ee
	s_mov_b32 s13, 0x40400000
	v_mul_f32_e64 v110, -v138, v85
	v_fma_f32 v84, 0, v168, v110
	v_fma_f32 v85, -v138, v85, v168
	v_fma_f32 v80, v80, s14, v84
	v_fma_f32 v81, v81, s14, v85
	v_fma_f32 v84, v168, s12, v110
	v_fma_f32 v85, v169, s13, v110
	s_mov_b32 s12, 0x41800000
	s_mov_b32 s13, 0x41880000
	v_fma_f32 v84, v82, s14, v84
	v_fma_f32 v85, v83, s14, v85
	v_fma_f32 v82, v168, s12, v110
	v_fma_f32 v83, v169, s13, v110
	s_mov_b32 s12, 0x41900000
	s_mov_b32 s13, 0x41980000
	v_fma_f32 v86, v86, s14, v82
	v_fma_f32 v87, v87, s14, v83
	v_fma_f32 v82, v168, s12, v110
	v_fma_f32 v83, v169, s13, v110
	s_mov_b32 s12, 0x42000000
	s_mov_b32 s13, 0x42040000
	v_fma_f32 v88, v88, s14, v82
	v_fma_f32 v89, v89, s14, v83
	v_fma_f32 v82, v168, s12, v110
	v_fma_f32 v83, v169, s13, v110
	s_mov_b32 s12, 0x42080000
	s_mov_b32 s13, 0x420c0000
	v_fma_f32 v90, v90, s14, v82
	v_fma_f32 v91, v91, s14, v83
	v_fma_f32 v82, v168, s12, v110
	v_fma_f32 v83, v169, s13, v110
	s_mov_b32 s12, 0x42400000
	s_mov_b32 s13, 0x42440000
	v_fma_f32 v92, v92, s14, v82
	v_fma_f32 v93, v93, s14, v83
	v_fma_f32 v82, v168, s12, v110
	v_fma_f32 v83, v169, s13, v110
	s_mov_b32 s12, 0x42480000
	s_mov_b32 s13, 0x424c0000
	v_fma_f32 v94, v106, s14, v82
	v_fma_f32 v95, v107, s14, v83
	v_fma_f32 v82, v168, s12, v110
	v_fma_f32 v83, v169, s13, v110
	s_nop 0
	v_fma_f32 v82, v108, s14, v82
	v_fma_f32 v83, v109, s14, v83
	s_cbranch_scc1 .LBB0_3786
	v_cmp_lt_i32_e32 vcc, -1, v96
	s_movk_i32 s11, 0xff
	s_nop 0
	v_cndmask_b32_e32 v80, v204, v80, vcc
	v_cmp_lt_i32_e32 vcc, 15, v96
	s_nop 1
	v_cndmask_b32_e32 v81, v204, v81, vcc
	v_cmp_lt_i32_e32 vcc, 31, v96
	s_nop 1
	v_cndmask_b32_e32 v84, v204, v84, vcc
	v_cmp_lt_i32_e32 vcc, 47, v96
	s_nop 1
	v_cndmask_b32_e32 v85, v204, v85, vcc
	v_cmp_lt_i32_e32 vcc, s11, v96
	s_movk_i32 s11, 0x10f
	s_nop 0
	v_cndmask_b32_e32 v86, v204, v86, vcc
	v_cmp_lt_i32_e32 vcc, s11, v96
	s_movk_i32 s11, 0x11f
	s_nop 0
	v_cndmask_b32_e32 v87, v204, v87, vcc
	v_cmp_lt_i32_e32 vcc, s11, v96
	s_movk_i32 s11, 0x12f
	s_nop 0
	v_cndmask_b32_e32 v88, v204, v88, vcc
	v_cmp_lt_i32_e32 vcc, s11, v96
	s_movk_i32 s11, 0x1ff
	s_nop 0
	v_cndmask_b32_e32 v89, v204, v89, vcc
	v_cmp_lt_i32_e32 vcc, s11, v96
	s_movk_i32 s11, 0x20f
	s_nop 0
	v_cndmask_b32_e32 v90, v204, v90, vcc
	v_cmp_lt_i32_e32 vcc, s11, v96
	s_movk_i32 s11, 0x21f
	s_nop 0
	v_cndmask_b32_e32 v91, v204, v91, vcc
	v_cmp_lt_i32_e32 vcc, s11, v96
	s_movk_i32 s11, 0x22f
	s_nop 0
	v_cndmask_b32_e32 v92, v204, v92, vcc
	v_cmp_lt_i32_e32 vcc, s11, v96
	s_movk_i32 s11, 0x2ff
	s_nop 0
	v_cndmask_b32_e32 v93, v204, v93, vcc
	v_cmp_lt_i32_e32 vcc, s11, v96
	s_movk_i32 s11, 0x30f
	s_nop 0
	v_cndmask_b32_e32 v94, v204, v94, vcc
	v_cmp_lt_i32_e32 vcc, s11, v96
	s_movk_i32 s11, 0x31f
	s_nop 0
	v_cndmask_b32_e32 v95, v204, v95, vcc
	v_cmp_lt_i32_e32 vcc, s11, v96
	s_movk_i32 s11, 0x32f
	s_nop 0
	v_cndmask_b32_e32 v82, v204, v82, vcc
	v_cmp_lt_i32_e32 vcc, s11, v96
	s_nop 1
	v_cndmask_b32_e32 v83, v204, v83, vcc
; __device__ __forceinline__ float shx(float v, int lane, int o) { return __builtin_bit_cast(float, __builtin_amdgcn_ds_bpermute((lane ^ o) << 2, __builtin_bit_cast(int, v))); }
; template <int MODE> ...
;     ...
;     const float sk = slope2 * (float)KS;
;     float alpha[2] = {1.f, 1.f};
; #pragma unroll
;     for (int ci = 0; ci < 2; ++ci) {
;         const int base = tpos[ci] - kp0 - KS * (fq * 4);
;         const float bb = -slope2 * (float)base;
;         float mx = NEGB;
; #pragma unroll
;         for (int k4 = 0; k4 < 4; ++k4)
; #pragma unroll
;             for (int j = 0; j < 4; ++j) {
;                 s[ci][k4][j] = __builtin_fmaf(s[ci][k4][j], QSCALE2, __builtin_fmaf(sk, (float)(k4 * 16 + j), bb)); }
;         if (MASK) {
; #pragma unroll
;             for (int k4 = 0; k4 < 4; ++k4)
; #pragma unroll
;                 for (int j = 0; j < 4; ++j) { const int c = KS * (k4 * 16 + j); bool ok = c <= base; if (MODE == 3) ok = ok && (base - c < 512); s[ci][k4][j] = ok ? s[ci][k4][j] : 2.0f * NEGB; } }
; #pragma unroll
;         for (int k4 = 0; k4 < 4; ++k4)
; #pragma unroll
;             for (int j = 0; j < 4; ++j) mx = fmaxf(mx, s[ci][k4][j]);
;         if (MODE == 2) mx = selbit[ci] ? mx : NEGB;
;         if (MODE != 1) {
;             mx = fmaxf(mx, shx(mx, lane, 16)); mx = fmaxf(mx, shx(mx, lane, 32));
.LBB0_3786:
	s_mov_b32 s11, 0xf149f2ca
	v_max3_f32 v96, v80, s11, v81
	v_max3_f32 v96, v96, v84, v85
	v_max3_f32 v96, v96, v86, v87
	v_cvt_f32_i32_e32 v97, v102
	v_max3_f32 v96, v96, v88, v89
	v_max3_f32 v96, v96, v90, v91
	v_max3_f32 v96, v96, v92, v93
	v_max3_f32 v96, v96, v94, v95
	v_mul_f32_e64 v108, -v138, v97
	s_mov_b32 s12, 2.0
	v_max3_f32 v106, v96, v82, v83
	v_fma_f32 v97, -v138, v97, v168
	v_fma_f32 v96, 0, v168, v108
	s_mov_b32 s13, 0x40400000
	v_fma_f32 v96, v64, s14, v96
	v_fma_f32 v97, v65, s14, v97
	v_fma_f32 v64, v168, s12, v108
	v_fma_f32 v65, v169, s13, v108
	s_mov_b32 s12, 0x41800000
	s_mov_b32 s13, 0x41880000
	ds_bpermute_b32 v107, v137, v106
	v_fma_f32 v66, v66, s14, v64
	v_fma_f32 v67, v67, s14, v65
	v_fma_f32 v64, v168, s12, v108
	v_fma_f32 v65, v169, s13, v108
	s_mov_b32 s12, 0x41900000
	s_mov_b32 s13, 0x41980000
	v_fma_f32 v64, v60, s14, v64
	v_fma_f32 v65, v61, s14, v65
	v_fma_f32 v60, v168, s12, v108
	v_fma_f32 v61, v169, s13, v108
	s_mov_b32 s12, 0x42000000
	s_mov_b32 s13, 0x42040000
	v_fma_f32 v62, v62, s14, v60
	v_fma_f32 v63, v63, s14, v61
	v_fma_f32 v60, v168, s12, v108
	v_fma_f32 v61, v169, s13, v108
	s_mov_b32 s12, 0x42080000
	s_waitcnt lgkmcnt(0)
	v_max_f32_e32 v107, v107, v107
	s_mov_b32 s13, 0x420c0000
	v_max_f32_e32 v106, v106, v107
	v_fma_f32 v60, v56, s14, v60
	v_fma_f32 v61, v57, s14, v61
	v_fma_f32 v56, v168, s12, v108
	v_fma_f32 v57, v169, s13, v108
	s_mov_b32 s12, 0x42400000
	ds_bpermute_b32 v107, v207, v106
	s_mov_b32 s13, 0x42440000
	v_fma_f32 v56, v58, s14, v56
	v_fma_f32 v57, v59, s14, v57
	v_fma_f32 v58, v168, s12, v108
	v_fma_f32 v59, v169, s13, v108
	s_mov_b32 s12, 0x42480000
	s_mov_b32 s13, 0x424c0000
	v_fma_f32 v52, v52, s14, v58
	v_fma_f32 v53, v53, s14, v59
	v_fma_f32 v58, v168, s12, v108
	v_fma_f32 v59, v169, s13, v108
	s_andn2_b64 vcc, exec, s[2:3]
	v_fma_f32 v54, v54, s14, v58
	v_fma_f32 v55, v55, s14, v59
	s_cbranch_vccnz .LBB0_3788
	v_cmp_lt_i32_e32 vcc, -1, v102
	s_movk_i32 s2, 0xff
	s_nop 0
	v_cndmask_b32_e32 v96, v204, v96, vcc
	v_cmp_lt_i32_e32 vcc, 15, v102
	s_nop 1
	v_cndmask_b32_e32 v97, v204, v97, vcc
	v_cmp_lt_i32_e32 vcc, 31, v102
	s_nop 1
	v_cndmask_b32_e32 v66, v204, v66, vcc
	v_cmp_lt_i32_e32 vcc, 47, v102
	s_nop 1
	v_cndmask_b32_e32 v67, v204, v67, vcc
	v_cmp_lt_i32_e32 vcc, s2, v102
	s_movk_i32 s2, 0x10f
	s_nop 0
	v_cndmask_b32_e32 v64, v204, v64, vcc
	v_cmp_lt_i32_e32 vcc, s2, v102
	s_movk_i32 s2, 0x11f
	s_nop 0
	v_cndmask_b32_e32 v65, v204, v65, vcc
	v_cmp_lt_i32_e32 vcc, s2, v102
	s_movk_i32 s2, 0x12f
	s_nop 0
	v_cndmask_b32_e32 v62, v204, v62, vcc
	v_cmp_lt_i32_e32 vcc, s2, v102
	s_movk_i32 s2, 0x1ff
	s_nop 0
	v_cndmask_b32_e32 v63, v204, v63, vcc
	v_cmp_lt_i32_e32 vcc, s2, v102
	s_movk_i32 s2, 0x20f
	s_nop 0
	v_cndmask_b32_e32 v60, v204, v60, vcc
	v_cmp_lt_i32_e32 vcc, s2, v102
	s_movk_i32 s2, 0x21f
	s_nop 0
	v_cndmask_b32_e32 v61, v204, v61, vcc
	v_cmp_lt_i32_e32 vcc, s2, v102
	s_movk_i32 s2, 0x22f
	s_nop 0
	v_cndmask_b32_e32 v56, v204, v56, vcc
	v_cmp_lt_i32_e32 vcc, s2, v102
	s_movk_i32 s2, 0x2ff
	s_nop 0
	v_cndmask_b32_e32 v57, v204, v57, vcc
	v_cmp_lt_i32_e32 vcc, s2, v102
	s_movk_i32 s2, 0x30f
	s_nop 0
	v_cndmask_b32_e32 v52, v204, v52, vcc
	v_cmp_lt_i32_e32 vcc, s2, v102
	s_movk_i32 s2, 0x31f
	s_nop 0
	v_cndmask_b32_e32 v53, v204, v53, vcc
	v_cmp_lt_i32_e32 vcc, s2, v102
	s_movk_i32 s2, 0x32f
	s_nop 0
	v_cndmask_b32_e32 v54, v204, v54, vcc
	v_cmp_lt_i32_e32 vcc, s2, v102
	s_nop 1
	v_cndmask_b32_e32 v55, v204, v55, vcc

; #define LAS __attribute__((address_space(3)))
; template <int MODE> ...
;     ...
;     {
;         const LAS unsigned char* kb = lds + AL_KT + fr * KT_PITCH + fq * 16;
;     ...
;         bf16x8 kr[4]; kr[0] = KFRAG(0); kr[1] = KFRAG(1); kr[2] = KFRAG(2);
; #pragma unroll
;         for (int i = 0; i < 16; ++i) {
;             if (i + 3 < 16) kr[(i + 3) & 3] = KFRAG(i + 3);
;             __builtin_amdgcn_sched_barrier(0);
;             s[0][i & 3] = __builtin_amdgcn_mfma_f32_16x16x32_bf16(kr[i & 3], qf[0][i >> 2], s[0][i & 3], 0, 0, 0);
;             s[1][i & 3] = __builtin_amdgcn_mfma_f32_16x16x32_bf16(kr[i & 3], qf[1][i >> 2], s[1][i & 3], 0, 0, 0);
;             __builtin_amdgcn_sched_barrier(0);
;         }
;     ...
;     }
;     const float sk = slope2 * (float)KS;
;     float alpha[2] = {1.f, 1.f};
; #pragma unroll
;     for (int ci = 0; ci < 2; ++ci) {
;         const int base = tpos[ci] - kp0 - KS * (fq * 4);
;         const float bb = -slope2 * (float)base;
;         float mx = NEGB;
; #pragma unroll
;         for (int k4 = 0; k4 < 4; ++k4)
; #pragma unroll
;             for (int j = 0; j < 4; ++j) {
;                 s[ci][k4][j] = __builtin_fmaf(s[ci][k4][j], QSCALE2, __builtin_fmaf(sk, (float)(k4 * 16 + j), bb)); }
;         if (MASK) {
; #pragma unroll
;             for (int k4 = 0; k4 < 4; ++k4)
; #pragma unroll
;                 for (int j = 0; j < 4; ++j) { const int c = KS * (k4 * 16 + j); bool ok = c <= base; if (MODE == 3) ok = ok && (base - c < 512); s[ci][k4][j] = ok ? s[ci][k4][j] : 2.0f * NEGB; } }
.LBB0_3798:
	v_add3_u32 v236, s9, v210, v136
	ds_read_b128 v[116:119], v236 offset:8704
	ds_read_b128 v[120:123], v236 offset:13056
	ds_read_b128 v[124:127], v236 offset:4352
	ds_read_b128 v[128:131], v236
	s_cmp_gt_i32 s8, s16
	s_cselect_b64 s[0:1], -1, 0
	s_cmp_le_i32 s8, s16
	s_waitcnt lgkmcnt(0)
	v_mfma_f32_16x16x32_bf16 v[176:179], v[128:131], v[4:7], 0
	v_mfma_f32_16x16x32_bf16 v[128:131], v[128:131], v[20:23], 0
	ds_read_b128 v[180:183], v236 offset:64
	v_mfma_f32_16x16x32_bf16 v[184:187], v[124:127], v[4:7], 0
	v_mfma_f32_16x16x32_bf16 v[124:127], v[124:127], v[20:23], 0
	ds_read_b128 v[188:191], v236 offset:4416
	v_mfma_f32_16x16x32_bf16 v[220:223], v[116:119], v[4:7], 0
	v_mfma_f32_16x16x32_bf16 v[116:119], v[116:119], v[20:23], 0
	ds_read_b128 v[224:227], v236 offset:8768
	v_mfma_f32_16x16x32_bf16 v[228:231], v[120:123], v[4:7], 0
	v_mfma_f32_16x16x32_bf16 v[120:123], v[120:123], v[20:23], 0
	ds_read_b128 v[232:235], v236 offset:13120
	s_waitcnt lgkmcnt(3)
	v_mfma_f32_16x16x32_bf16 v[176:179], v[180:183], v[8:11], v[176:179]
	v_mfma_f32_16x16x32_bf16 v[128:131], v[180:183], v[24:27], v[128:131]
	ds_read_b128 v[180:183], v236 offset:128
	s_waitcnt lgkmcnt(3)
	v_mfma_f32_16x16x32_bf16 v[184:187], v[188:191], v[8:11], v[184:187]
	v_mfma_f32_16x16x32_bf16 v[124:127], v[188:191], v[24:27], v[124:127]
	ds_read_b128 v[188:191], v236 offset:4480
	s_waitcnt lgkmcnt(3)
	v_mfma_f32_16x16x32_bf16 v[220:223], v[224:227], v[8:11], v[220:223]
	v_mfma_f32_16x16x32_bf16 v[116:119], v[224:227], v[24:27], v[116:119]
	ds_read_b128 v[224:227], v236 offset:8832
	s_waitcnt lgkmcnt(3)
	v_mfma_f32_16x16x32_bf16 v[120:123], v[232:235], v[24:27], v[120:123]
	v_mfma_f32_16x16x32_bf16 v[228:231], v[232:235], v[8:11], v[228:231]
	ds_read_b128 v[232:235], v236 offset:13184
	s_waitcnt lgkmcnt(3)
	v_mfma_f32_16x16x32_bf16 v[176:179], v[180:183], v[12:15], v[176:179]
	v_mfma_f32_16x16x32_bf16 v[128:131], v[180:183], v[28:31], v[128:131]
	ds_read_b128 v[180:183], v236 offset:192
	s_waitcnt lgkmcnt(3)
	v_mfma_f32_16x16x32_bf16 v[184:187], v[188:191], v[12:15], v[184:187]
	v_mfma_f32_16x16x32_bf16 v[124:127], v[188:191], v[28:31], v[124:127]
	ds_read_b128 v[188:191], v236 offset:4544
	s_waitcnt lgkmcnt(3)
	v_mfma_f32_16x16x32_bf16 v[220:223], v[224:227], v[12:15], v[220:223]
	v_mfma_f32_16x16x32_bf16 v[116:119], v[224:227], v[28:31], v[116:119]
	ds_read_b128 v[224:227], v236 offset:8896
	s_waitcnt lgkmcnt(3)
	v_mfma_f32_16x16x32_bf16 v[228:231], v[232:235], v[12:15], v[228:231]
	v_mfma_f32_16x16x32_bf16 v[232:235], v[232:235], v[28:31], v[120:123]
	ds_read_b128 v[236:239], v236 offset:13248
	s_waitcnt lgkmcnt(3)
	v_mfma_f32_16x16x32_bf16 v[176:179], v[180:183], v[16:19], v[176:179]
	v_mfma_f32_16x16x32_bf16 v[128:131], v[180:183], v[32:35], v[128:131]
	s_waitcnt lgkmcnt(2)
	v_mfma_f32_16x16x32_bf16 v[180:183], v[188:191], v[16:19], v[184:187]
	v_mfma_f32_16x16x32_bf16 v[124:127], v[188:191], v[32:35], v[124:127]
	s_waitcnt lgkmcnt(1)
	v_mfma_f32_16x16x32_bf16 v[120:123], v[224:227], v[32:35], v[116:119]
	v_mfma_f32_16x16x32_bf16 v[240:243], v[224:227], v[16:19], v[220:223]
	s_waitcnt lgkmcnt(0)
	v_mfma_f32_16x16x32_bf16 v[116:119], v[236:239], v[32:35], v[232:235]
	v_mfma_f32_16x16x32_bf16 v[222:225], v[236:239], v[16:19], v[228:231]
	v_add_u32_e32 v220, -4, v219
	v_cvt_f32_i32_e32 v185, v220
	s_mov_b32 s2, 2.0
	s_mov_b32 s12, 0x3e0293ee
	s_mov_b32 s3, 0x40400000
	v_mul_f32_e64 v226, -v138, v185
	v_fma_f32 v184, 0, v168, v226
	v_fma_f32 v185, -v138, v185, v168
	v_fma_f32 v188, v176, s12, v184
	v_fma_f32 v189, v177, s12, v185
	v_fma_f32 v176, v168, s2, v226
	v_fma_f32 v177, v169, s3, v226
	s_mov_b32 s2, 0x41800000
	s_mov_b32 s3, 0x41880000
	v_fma_f32 v190, v178, s12, v176
	v_fma_f32 v191, v179, s12, v177
	v_fma_f32 v176, v168, s2, v226
	v_fma_f32 v177, v169, s3, v226
	s_mov_b32 s2, 0x41900000
	s_mov_b32 s3, 0x41980000
	v_fma_f32 v186, v180, s12, v176
	v_fma_f32 v187, v181, s12, v177
	v_fma_f32 v176, v168, s2, v226
	v_fma_f32 v177, v169, s3, v226
	s_mov_b32 s2, 0x42000000
	s_mov_b32 s3, 0x42040000
	v_fma_f32 v184, v182, s12, v176
	v_fma_f32 v185, v183, s12, v177
	v_fma_f32 v176, v168, s2, v226
	v_fma_f32 v177, v169, s3, v226
	s_mov_b32 s2, 0x42080000
	s_mov_b32 s3, 0x420c0000
	v_fma_f32 v182, v240, s12, v176
	v_fma_f32 v183, v241, s12, v177
	v_fma_f32 v176, v168, s2, v226
	v_fma_f32 v177, v169, s3, v226
	s_mov_b32 s2, 0x42400000
	s_mov_b32 s3, 0x42440000
	v_fma_f32 v180, v242, s12, v176
	v_fma_f32 v181, v243, s12, v177
	v_fma_f32 v176, v168, s2, v226
	v_fma_f32 v177, v169, s3, v226
	s_mov_b32 s2, 0x42480000
	s_mov_b32 s3, 0x424c0000
	v_fma_f32 v178, v222, s12, v176
	v_fma_f32 v179, v223, s12, v177
	v_fma_f32 v176, v168, s2, v226
	v_fma_f32 v177, v169, s3, v226
	s_nop 0
	v_fma_f32 v176, v224, s12, v176
	v_fma_f32 v177, v225, s12, v177
	s_cbranch_scc1 .LBB0_3800
	v_cmp_lt_i32_e32 vcc, -1, v220
	s_movk_i32 s2, 0xff
	s_nop 0
	v_cndmask_b32_e32 v188, v204, v188, vcc
	v_cmp_lt_i32_e32 vcc, 15, v220
	s_nop 1
	v_cndmask_b32_e32 v189, v204, v189, vcc
	v_cmp_lt_i32_e32 vcc, 31, v220
	s_nop 1
	v_cndmask_b32_e32 v190, v204, v190, vcc
	v_cmp_lt_i32_e32 vcc, 47, v220
	s_nop 1
	v_cndmask_b32_e32 v191, v204, v191, vcc
	v_cmp_lt_i32_e32 vcc, s2, v220
	s_movk_i32 s2, 0x10f
	s_nop 0
	v_cndmask_b32_e32 v186, v204, v186, vcc
	v_cmp_lt_i32_e32 vcc, s2, v220
	s_movk_i32 s2, 0x11f
	s_nop 0
	v_cndmask_b32_e32 v187, v204, v187, vcc
	v_cmp_lt_i32_e32 vcc, s2, v220
	s_movk_i32 s2, 0x12f
	s_nop 0
	v_cndmask_b32_e32 v184, v204, v184, vcc
	v_cmp_lt_i32_e32 vcc, s2, v220
	s_movk_i32 s2, 0x1ff
	s_nop 0
	v_cndmask_b32_e32 v185, v204, v185, vcc
	v_cmp_lt_i32_e32 vcc, s2, v220
	s_movk_i32 s2, 0x20f
	s_nop 0
	v_cndmask_b32_e32 v182, v204, v182, vcc
	v_cmp_lt_i32_e32 vcc, s2, v220
	s_movk_i32 s2, 0x21f
	s_nop 0
	v_cndmask_b32_e32 v183, v204, v183, vcc
	v_cmp_lt_i32_e32 vcc, s2, v220
	s_movk_i32 s2, 0x22f
	s_nop 0
	v_cndmask_b32_e32 v180, v204, v180, vcc
	v_cmp_lt_i32_e32 vcc, s2, v220
	s_movk_i32 s2, 0x2ff
	s_nop 0
	v_cndmask_b32_e32 v181, v204, v181, vcc
	v_cmp_lt_i32_e32 vcc, s2, v220
	s_movk_i32 s2, 0x30f
	s_nop 0
	v_cndmask_b32_e32 v178, v204, v178, vcc
	v_cmp_lt_i32_e32 vcc, s2, v220
	s_movk_i32 s2, 0x31f
	s_nop 0
	v_cndmask_b32_e32 v179, v204, v179, vcc
	v_cmp_lt_i32_e32 vcc, s2, v220
	s_movk_i32 s2, 0x32f
	s_nop 0
	v_cndmask_b32_e32 v176, v204, v176, vcc
	v_cmp_lt_i32_e32 vcc, s2, v220
	s_nop 1
	v_cndmask_b32_e32 v177, v204, v177, vcc

; template <int MODE> ...
;     ...
;     const float sk = slope2 * (float)KS;
;     float alpha[2] = {1.f, 1.f};
; #pragma unroll
;     for (int ci = 0; ci < 2; ++ci) {
;         const int base = tpos[ci] - kp0 - KS * (fq * 4);
;         const float bb = -slope2 * (float)base;
;         float mx = NEGB;
; #pragma unroll
;         for (int k4 = 0; k4 < 4; ++k4)
; #pragma unroll
;             for (int j = 0; j < 4; ++j) {
;                 s[ci][k4][j] = __builtin_fmaf(s[ci][k4][j], QSCALE2, __builtin_fmaf(sk, (float)(k4 * 16 + j), bb)); }
;         if (MASK) {
; #pragma unroll
;             for (int k4 = 0; k4 < 4; ++k4)
; #pragma unroll
;                 for (int j = 0; j < 4; ++j) { const int c = KS * (k4 * 16 + j); bool ok = c <= base; if (MODE == 3) ok = ok && (base - c < 512); s[ci][k4][j] = ok ? s[ci][k4][j] : 2.0f * NEGB; } }
.LBB0_3808:
	s_or_b64 exec, exec, s[2:3]
	s_waitcnt lgkmcnt(1)
	v_cvt_f32_i32_e32 v177, v219
	s_mov_b32 s2, 2.0
	s_mov_b32 s3, 0x40400000
	s_andn2_b64 vcc, exec, s[0:1]
	s_waitcnt lgkmcnt(0)
	v_mul_f32_e64 v224, -v138, v177
	v_fma_f32 v176, 0, v168, v224
	v_fma_f32 v177, -v138, v177, v168
	v_fma_f32 v176, v128, s12, v176
	v_fma_f32 v177, v129, s12, v177
	v_fma_f32 v128, v168, s2, v224
	v_fma_f32 v129, v169, s3, v224
	s_mov_b32 s2, 0x41800000
	s_mov_b32 s3, 0x41880000
	v_fma_f32 v130, v130, s12, v128
	v_fma_f32 v131, v131, s12, v129
	v_fma_f32 v128, v168, s2, v224
	v_fma_f32 v129, v169, s3, v224
	s_mov_b32 s2, 0x41900000
	s_mov_b32 s3, 0x41980000
	v_fma_f32 v128, v124, s12, v128
	v_fma_f32 v129, v125, s12, v129
	v_fma_f32 v124, v168, s2, v224
	v_fma_f32 v125, v169, s3, v224
	s_mov_b32 s2, 0x42000000
	s_mov_b32 s3, 0x42040000
	v_fma_f32 v126, v126, s12, v124
	v_fma_f32 v127, v127, s12, v125
	v_fma_f32 v124, v168, s2, v224
	v_fma_f32 v125, v169, s3, v224
	s_mov_b32 s2, 0x42080000
	s_mov_b32 s3, 0x420c0000
	v_fma_f32 v124, v120, s12, v124
	v_fma_f32 v125, v121, s12, v125
	v_fma_f32 v120, v168, s2, v224
	v_fma_f32 v121, v169, s3, v224
	s_mov_b32 s2, 0x42400000
	s_mov_b32 s3, 0x42440000
	v_fma_f32 v122, v122, s12, v120
	v_fma_f32 v123, v123, s12, v121
	v_fma_f32 v120, v168, s2, v224
	v_fma_f32 v121, v169, s3, v224
	s_mov_b32 s2, 0x42480000
	s_mov_b32 s3, 0x424c0000
	v_fma_f32 v120, v116, s12, v120
	v_fma_f32 v121, v117, s12, v121
	v_fma_f32 v116, v168, s2, v224
	v_fma_f32 v117, v169, s3, v224
	s_nop 0
	v_fma_f32 v116, v118, s12, v116
	v_fma_f32 v117, v119, s12, v117
	s_cbranch_vccnz .LBB0_3810
	v_cmp_lt_i32_e32 vcc, -1, v219
	s_movk_i32 s0, 0xff
	s_nop 0
	v_cndmask_b32_e32 v176, v204, v176, vcc
	v_cmp_lt_i32_e32 vcc, 15, v219
	s_nop 1
	v_cndmask_b32_e32 v177, v204, v177, vcc
	v_cmp_lt_i32_e32 vcc, 31, v219
	s_nop 1
	v_cndmask_b32_e32 v130, v204, v130, vcc
	v_cmp_lt_i32_e32 vcc, 47, v219
	s_nop 1
	v_cndmask_b32_e32 v131, v204, v131, vcc
	v_cmp_lt_i32_e32 vcc, s0, v219
	s_movk_i32 s0, 0x10f
	s_nop 0
	v_cndmask_b32_e32 v128, v204, v128, vcc
	v_cmp_lt_i32_e32 vcc, s0, v219
	s_movk_i32 s0, 0x11f
	s_nop 0
	v_cndmask_b32_e32 v129, v204, v129, vcc
	v_cmp_lt_i32_e32 vcc, s0, v219
	s_movk_i32 s0, 0x12f
	s_nop 0
	v_cndmask_b32_e32 v126, v204, v126, vcc
	v_cmp_lt_i32_e32 vcc, s0, v219
	s_movk_i32 s0, 0x1ff
	s_nop 0
	v_cndmask_b32_e32 v127, v204, v127, vcc
	v_cmp_lt_i32_e32 vcc, s0, v219
	s_movk_i32 s0, 0x20f
	s_nop 0
	v_cndmask_b32_e32 v124, v204, v124, vcc
	v_cmp_lt_i32_e32 vcc, s0, v219
	s_movk_i32 s0, 0x21f
	s_nop 0
	v_cndmask_b32_e32 v125, v204, v125, vcc
	v_cmp_lt_i32_e32 vcc, s0, v219
	s_movk_i32 s0, 0x22f
	s_nop 0
	v_cndmask_b32_e32 v122, v204, v122, vcc
	v_cmp_lt_i32_e32 vcc, s0, v219
	s_movk_i32 s0, 0x2ff
	s_nop 0
	v_cndmask_b32_e32 v123, v204, v123, vcc
	v_cmp_lt_i32_e32 vcc, s0, v219
	s_movk_i32 s0, 0x30f
	s_nop 0
	v_cndmask_b32_e32 v120, v204, v120, vcc
	v_cmp_lt_i32_e32 vcc, s0, v219
	s_movk_i32 s0, 0x31f
	s_nop 0
	v_cndmask_b32_e32 v121, v204, v121, vcc
	v_cmp_lt_i32_e32 vcc, s0, v219
	s_movk_i32 s0, 0x32f
	s_nop 0
	v_cndmask_b32_e32 v116, v204, v116, vcc
	v_cmp_lt_i32_e32 vcc, s0, v219
	s_nop 1
	v_cndmask_b32_e32 v117, v204, v117, vcc

; #define LAS __attribute__((address_space(3)))
; template <int MODE> ...
;     ...
;     {
;         const LAS unsigned char* kb = lds + AL_KT + fr * KT_PITCH + fq * 16;
;     ...
;         bf16x8 kr[4]; kr[0] = KFRAG(0); kr[1] = KFRAG(1); kr[2] = KFRAG(2);
; #pragma unroll
;         for (int i = 0; i < 16; ++i) {
;             if (i + 3 < 16) kr[(i + 3) & 3] = KFRAG(i + 3);
;             __builtin_amdgcn_sched_barrier(0);
;             s[0][i & 3] = __builtin_amdgcn_mfma_f32_16x16x32_bf16(kr[i & 3], qf[0][i >> 2], s[0][i & 3], 0, 0, 0);
;             s[1][i & 3] = __builtin_amdgcn_mfma_f32_16x16x32_bf16(kr[i & 3], qf[1][i >> 2], s[1][i & 3], 0, 0, 0);
;             __builtin_amdgcn_sched_barrier(0);
;         }
;     ...
;     }
;     const float sk = slope2 * (float)KS;
;     float alpha[2] = {1.f, 1.f};
; #pragma unroll
;     for (int ci = 0; ci < 2; ++ci) {
;         const int base = tpos[ci] - kp0 - KS * (fq * 4);
;         const float bb = -slope2 * (float)base;
;         float mx = NEGB;
; #pragma unroll
;         for (int k4 = 0; k4 < 4; ++k4)
; #pragma unroll
;             for (int j = 0; j < 4; ++j) {
;                 s[ci][k4][j] = __builtin_fmaf(s[ci][k4][j], QSCALE2, __builtin_fmaf(sk, (float)(k4 * 16 + j), bb)); }
;         if (MASK) {
; #pragma unroll
;             for (int k4 = 0; k4 < 4; ++k4)
; #pragma unroll
;                 for (int j = 0; j < 4; ++j) { const int c = KS * (k4 * 16 + j); bool ok = c <= base; if (MODE == 3) ok = ok && (base - c < 512); s[ci][k4][j] = ok ? s[ci][k4][j] : 2.0f * NEGB; } }
; __device__ __forceinline__ void nsa_item(LAS unsigned char* lds, int b, int g, int tq, const bf16_t* Q, const bf16_t* KS, const bf16_t* VST, const bf16_t* KW, const bf16_t* VWT,
;                                          const bf16_t* KCMP, const bf16_t* VCMPT, const float* GL, bf16_t* YB) {
;     ...
;             if ((wun >> j) & 1ull) { selbit[0] = (selm[0] >> j) & 1ull; selbit[1] = (selm[1] >> j) & 1ull;
;                 attn_tile<2>(j == tq, kvb, lds, qf, O, m, l, tpos, slope2, j * 64, selbit, fr, fq, wv, 0, lane); }
.LBB0_3833:
	s_lshr_b64 s[0:1], s[6:7], s4
	s_and_b32 s54, s0, 1
	s_cmp_eq_u64 s[54:55], 0
	s_cbranch_scc1 .LBB0_3829
	v_add3_u32 v1, s15, v210, v136
	ds_read_b128 v[120:123], v1 offset:8704
	ds_read_b128 v[124:127], v1 offset:13056
	ds_read_b128 v[128:131], v1 offset:4352
	ds_read_b128 v[132:135], v1
	v_readlane_b32 s0, v249, 42
	s_cmp_eq_u32 s4, s0
	s_cselect_b64 s[2:3], -1, 0
	v_readlane_b32 s1, v249, 43
	s_lshl_b32 s0, s4, 6
	s_waitcnt lgkmcnt(0)
	v_mfma_f32_16x16x32_bf16 v[178:181], v[132:135], v[4:7], 0
	v_mfma_f32_16x16x32_bf16 v[132:135], v[132:135], v[20:23], 0
	ds_read_b128 v[182:185], v1 offset:64
	v_mfma_f32_16x16x32_bf16 v[186:189], v[128:131], v[4:7], 0
	v_mfma_f32_16x16x32_bf16 v[128:131], v[128:131], v[20:23], 0
	ds_read_b128 v[190:193], v1 offset:4416
	v_mfma_f32_16x16x32_bf16 v[220:223], v[120:123], v[4:7], 0
	v_mfma_f32_16x16x32_bf16 v[120:123], v[120:123], v[20:23], 0
	ds_read_b128 v[224:227], v1 offset:8768
	v_mfma_f32_16x16x32_bf16 v[228:231], v[124:127], v[4:7], 0
	v_mfma_f32_16x16x32_bf16 v[124:127], v[124:127], v[20:23], 0
	ds_read_b128 v[232:235], v1 offset:13120
	s_waitcnt lgkmcnt(3)
	v_mfma_f32_16x16x32_bf16 v[178:181], v[182:185], v[8:11], v[178:181]
	v_mfma_f32_16x16x32_bf16 v[132:135], v[182:185], v[24:27], v[132:135]
	ds_read_b128 v[182:185], v1 offset:128
	s_waitcnt lgkmcnt(3)
	v_mfma_f32_16x16x32_bf16 v[186:189], v[190:193], v[8:11], v[186:189]
	v_mfma_f32_16x16x32_bf16 v[128:131], v[190:193], v[24:27], v[128:131]
	ds_read_b128 v[190:193], v1 offset:4480
	s_waitcnt lgkmcnt(3)
	v_mfma_f32_16x16x32_bf16 v[120:123], v[224:227], v[24:27], v[120:123]
	v_mfma_f32_16x16x32_bf16 v[220:223], v[224:227], v[8:11], v[220:223]
	ds_read_b128 v[224:227], v1 offset:8832
	s_waitcnt lgkmcnt(3)
	v_mfma_f32_16x16x32_bf16 v[124:127], v[232:235], v[24:27], v[124:127]
	v_mfma_f32_16x16x32_bf16 v[228:231], v[232:235], v[8:11], v[228:231]
	ds_read_b128 v[232:235], v1 offset:13184
	s_waitcnt lgkmcnt(3)
	v_mfma_f32_16x16x32_bf16 v[178:181], v[182:185], v[12:15], v[178:181]
	v_mfma_f32_16x16x32_bf16 v[132:135], v[182:185], v[28:31], v[132:135]
	ds_read_b128 v[182:185], v1 offset:192
	s_waitcnt lgkmcnt(3)
	v_mfma_f32_16x16x32_bf16 v[186:189], v[190:193], v[12:15], v[186:189]
	v_mfma_f32_16x16x32_bf16 v[128:131], v[190:193], v[28:31], v[128:131]
	ds_read_b128 v[190:193], v1 offset:4544
	s_waitcnt lgkmcnt(3)
	v_mfma_f32_16x16x32_bf16 v[120:123], v[224:227], v[28:31], v[120:123]
	v_mfma_f32_16x16x32_bf16 v[220:223], v[224:227], v[12:15], v[220:223]
	ds_read_b128 v[224:227], v1 offset:8896
	s_waitcnt lgkmcnt(3)
	v_mfma_f32_16x16x32_bf16 v[228:231], v[232:235], v[12:15], v[228:231]
	v_mfma_f32_16x16x32_bf16 v[232:235], v[232:235], v[28:31], v[124:127]
	ds_read_b128 v[236:239], v1 offset:13248
	s_waitcnt lgkmcnt(3)
	v_mfma_f32_16x16x32_bf16 v[178:181], v[182:185], v[16:19], v[178:181]
	v_mfma_f32_16x16x32_bf16 v[132:135], v[182:185], v[32:35], v[132:135]
	s_waitcnt lgkmcnt(2)
	v_mfma_f32_16x16x32_bf16 v[182:185], v[190:193], v[16:19], v[186:189]
	v_mfma_f32_16x16x32_bf16 v[128:131], v[190:193], v[32:35], v[128:131]
	s_waitcnt lgkmcnt(1)
	v_mfma_f32_16x16x32_bf16 v[124:127], v[224:227], v[32:35], v[120:123]
	v_mfma_f32_16x16x32_bf16 v[220:223], v[224:227], v[16:19], v[220:223]
	s_waitcnt lgkmcnt(0)
	v_mfma_f32_16x16x32_bf16 v[120:123], v[236:239], v[32:35], v[232:235]
	v_mfma_f32_16x16x32_bf16 v[224:227], v[236:239], v[16:19], v[228:231]
	v_subrev_u32_e32 v1, s0, v219
	v_add_u32_e32 v192, v1, v218
	v_cvt_f32_i32_e32 v3, v192
	s_mov_b32 s0, 2.0
	s_mov_b32 s16, 0x3e0293ee
	s_mov_b32 s1, 0x40400000
	v_mul_f32_e64 v2, -v138, v3
	v_fma_f32 v186, 0, v138, v2
	v_fma_f32 v187, -v138, v3, v138
	v_fma_f32 v188, v178, s16, v186
	v_fma_f32 v189, v179, s16, v187
	v_fma_f32 v178, v138, s0, v2
	v_fma_f32 v179, v139, s1, v2
	s_mov_b32 s0, 0x41800000
	s_mov_b32 s1, 0x41880000
	v_fma_f32 v190, v180, s16, v178
	v_fma_f32 v191, v181, s16, v179
	v_fma_f32 v178, v138, s0, v2
	v_fma_f32 v179, v139, s1, v2
	s_mov_b32 s0, 0x41900000
	s_mov_b32 s1, 0x41980000
	v_fma_f32 v186, v182, s16, v178
	v_fma_f32 v187, v183, s16, v179
	v_fma_f32 v178, v138, s0, v2
	v_fma_f32 v179, v139, s1, v2
	s_mov_b32 s0, 0x42000000
	s_mov_b32 s1, 0x42040000
	v_fma_f32 v184, v184, s16, v178
	v_fma_f32 v185, v185, s16, v179
	v_fma_f32 v178, v138, s0, v2
	v_fma_f32 v179, v139, s1, v2
	s_mov_b32 s0, 0x42080000
	s_mov_b32 s1, 0x420c0000
	v_fma_f32 v182, v220, s16, v178
	v_fma_f32 v183, v221, s16, v179
	v_fma_f32 v178, v138, s0, v2
	v_fma_f32 v179, v139, s1, v2
	s_mov_b32 s0, 0x42400000
	s_mov_b32 s1, 0x42440000
	v_fma_f32 v180, v222, s16, v178
	v_fma_f32 v181, v223, s16, v179
	v_fma_f32 v178, v138, s0, v2
	v_fma_f32 v179, v139, s1, v2
	s_mov_b32 s0, 0x42480000
	s_mov_b32 s1, 0x424c0000
	v_fma_f32 v3, v139, s1, v2
	v_fma_f32 v2, v138, s0, v2
	v_fma_f32 v178, v224, s16, v178
	v_fma_f32 v179, v225, s16, v179
	v_fma_f32 v2, v226, s16, v2
	v_fma_f32 v3, v227, s16, v3
	s_and_b64 vcc, exec, s[2:3]
	s_cbranch_vccz .LBB0_3836
	v_cmp_lt_i32_e32 vcc, -1, v192
	s_nop 1
	v_cndmask_b32_e32 v188, v204, v188, vcc
	v_cmp_lt_i32_e32 vcc, 0, v192
	s_nop 1
	v_cndmask_b32_e32 v189, v204, v189, vcc
	v_cmp_lt_i32_e32 vcc, 1, v192
	s_nop 1
	v_cndmask_b32_e32 v190, v204, v190, vcc
	v_cmp_lt_i32_e32 vcc, 2, v192
	s_nop 1
	v_cndmask_b32_e32 v191, v204, v191, vcc
	v_cmp_lt_i32_e32 vcc, 15, v192
	s_nop 1
	v_cndmask_b32_e32 v186, v204, v186, vcc
	v_cmp_lt_i32_e32 vcc, 16, v192
	s_nop 1
	v_cndmask_b32_e32 v187, v204, v187, vcc
	v_cmp_lt_i32_e32 vcc, 17, v192
	s_nop 1
	v_cndmask_b32_e32 v184, v204, v184, vcc
	v_cmp_lt_i32_e32 vcc, 18, v192
	s_nop 1
	v_cndmask_b32_e32 v185, v204, v185, vcc
	v_cmp_lt_i32_e32 vcc, 31, v192
	s_nop 1
	v_cndmask_b32_e32 v182, v204, v182, vcc
	v_cmp_lt_i32_e32 vcc, 32, v192
	s_nop 1
	v_cndmask_b32_e32 v183, v204, v183, vcc
	v_cmp_lt_i32_e32 vcc, 33, v192
	s_nop 1
	v_cndmask_b32_e32 v180, v204, v180, vcc
	v_cmp_lt_i32_e32 vcc, 34, v192
	s_nop 1
	v_cndmask_b32_e32 v181, v204, v181, vcc
	v_cmp_lt_i32_e32 vcc, 47, v192
	s_nop 1
	v_cndmask_b32_e32 v178, v204, v178, vcc
	v_cmp_lt_i32_e32 vcc, 48, v192
	s_nop 1
	v_cndmask_b32_e32 v179, v204, v179, vcc
	v_cmp_lt_i32_e32 vcc, 49, v192
	s_nop 1
	v_cndmask_b32_e32 v2, v204, v2, vcc
	v_cmp_lt_i32_e32 vcc, 50, v192
	s_nop 1
	v_cndmask_b32_e32 v3, v204, v3, vcc
; __device__ __forceinline__ float shx(float v, int lane, int o) { return __builtin_bit_cast(float, __builtin_amdgcn_ds_bpermute((lane ^ o) << 2, __builtin_bit_cast(int, v))); }
; template <int MODE> ...
;     ...
;     const float sk = slope2 * (float)KS;
;     float alpha[2] = {1.f, 1.f};
; #pragma unroll
;     for (int ci = 0; ci < 2; ++ci) {
;         const int base = tpos[ci] - kp0 - KS * (fq * 4);
;         const float bb = -slope2 * (float)base;
;         float mx = NEGB;
; #pragma unroll
;         for (int k4 = 0; k4 < 4; ++k4)
; #pragma unroll
;             for (int j = 0; j < 4; ++j) {
;                 s[ci][k4][j] = __builtin_fmaf(s[ci][k4][j], QSCALE2, __builtin_fmaf(sk, (float)(k4 * 16 + j), bb)); }
;         if (MASK) {
; #pragma unroll
;             for (int k4 = 0; k4 < 4; ++k4)
; #pragma unroll
;                 for (int j = 0; j < 4; ++j) { const int c = KS * (k4 * 16 + j); bool ok = c <= base; if (MODE == 3) ok = ok && (base - c < 512); s[ci][k4][j] = ok ? s[ci][k4][j] : 2.0f * NEGB; } }
; #pragma unroll
;         for (int k4 = 0; k4 < 4; ++k4)
; #pragma unroll
;             for (int j = 0; j < 4; ++j) mx = fmaxf(mx, s[ci][k4][j]);
;         if (MODE == 2) mx = selbit[ci] ? mx : NEGB;
;         if (MODE != 1) {
;             mx = fmaxf(mx, shx(mx, lane, 16)); mx = fmaxf(mx, shx(mx, lane, 32));
.LBB0_3836:
	v_lshrrev_b64 v[192:193], s4, v[104:105]
	s_mov_b32 s0, 0xf149f2ca
	v_max3_f32 v193, v188, s0, v189
	v_max3_f32 v193, v193, v190, v191
	v_max3_f32 v193, v193, v186, v187
	v_max3_f32 v193, v193, v184, v185
	v_max3_f32 v193, v193, v182, v183
	v_max3_f32 v193, v193, v180, v181
	v_and_b32_e32 v192, 1, v192
	v_max3_f32 v193, v193, v178, v179
	v_max3_f32 v193, v193, v2, v3
	v_cmp_eq_u32_e64 s[0:1], 1, v192
	v_add_u32_e32 v221, v1, v217
	v_cvt_f32_i32_e32 v223, v221
	v_cndmask_b32_e64 v192, v205, v193, s[0:1]
	ds_bpermute_b32 v193, v137, v192
	s_mov_b32 s16, 2.0
	v_mul_f32_e64 v222, -v138, v223
	s_mov_b32 s18, 0x3e0293ee
	s_mov_b32 s17, 0x40400000
	s_waitcnt lgkmcnt(0)
	v_max_f32_e32 v1, v193, v193
	v_max_f32_e32 v1, v192, v1
	v_fma_f32 v192, 0, v138, v222
	v_fma_f32 v193, -v138, v223, v138
	v_fma_f32 v192, v132, s18, v192
	v_fma_f32 v193, v133, s18, v193
	v_fma_f32 v132, v138, s16, v222
	v_fma_f32 v133, v139, s17, v222
	s_mov_b32 s16, 0x41800000
	s_mov_b32 s17, 0x41880000
	v_fma_f32 v134, v134, s18, v132
	v_fma_f32 v135, v135, s18, v133
	v_fma_f32 v132, v138, s16, v222
	v_fma_f32 v133, v139, s17, v222
	s_mov_b32 s16, 0x41900000
	s_mov_b32 s17, 0x41980000
	v_fma_f32 v132, v128, s18, v132
	v_fma_f32 v133, v129, s18, v133
	v_fma_f32 v128, v138, s16, v222
	v_fma_f32 v129, v139, s17, v222
	s_mov_b32 s16, 0x42000000
	s_mov_b32 s17, 0x42040000
	v_fma_f32 v130, v130, s18, v128
	v_fma_f32 v131, v131, s18, v129
	v_fma_f32 v128, v138, s16, v222
	v_fma_f32 v129, v139, s17, v222
	s_mov_b32 s16, 0x42080000
	s_mov_b32 s17, 0x420c0000
	v_fma_f32 v128, v124, s18, v128
	v_fma_f32 v129, v125, s18, v129
	v_fma_f32 v124, v138, s16, v222
	v_fma_f32 v125, v139, s17, v222
	s_mov_b32 s16, 0x42400000
	ds_bpermute_b32 v220, v207, v1
	s_mov_b32 s17, 0x42440000
	v_fma_f32 v126, v126, s18, v124
	v_fma_f32 v127, v127, s18, v125
	v_fma_f32 v124, v138, s16, v222
	v_fma_f32 v125, v139, s17, v222
	s_mov_b32 s16, 0x42480000
	s_mov_b32 s17, 0x424c0000
	v_fma_f32 v124, v120, s18, v124
	v_fma_f32 v125, v121, s18, v125
	v_fma_f32 v120, v138, s16, v222
	v_fma_f32 v121, v139, s17, v222
	s_andn2_b64 vcc, exec, s[2:3]
	v_fma_f32 v122, v122, s18, v120
	v_fma_f32 v123, v123, s18, v121
	s_mov_b32 s16, s19
	s_cbranch_vccnz .LBB0_3838
	v_cmp_lt_i32_e32 vcc, -1, v221
	s_nop 1
	v_cndmask_b32_e32 v192, v204, v192, vcc
	v_cmp_lt_i32_e32 vcc, 0, v221
	s_nop 1
	v_cndmask_b32_e32 v193, v204, v193, vcc
	v_cmp_lt_i32_e32 vcc, 1, v221
	s_nop 1
	v_cndmask_b32_e32 v134, v204, v134, vcc
	v_cmp_lt_i32_e32 vcc, 2, v221
	s_nop 1
	v_cndmask_b32_e32 v135, v204, v135, vcc
	v_cmp_lt_i32_e32 vcc, 15, v221
	s_nop 1
	v_cndmask_b32_e32 v132, v204, v132, vcc
	v_cmp_lt_i32_e32 vcc, 16, v221
	s_nop 1
	v_cndmask_b32_e32 v133, v204, v133, vcc
	v_cmp_lt_i32_e32 vcc, 17, v221
	s_nop 1
	v_cndmask_b32_e32 v130, v204, v130, vcc
	v_cmp_lt_i32_e32 vcc, 18, v221
	s_nop 1
	v_cndmask_b32_e32 v131, v204, v131, vcc
	v_cmp_lt_i32_e32 vcc, 31, v221
	s_nop 1
	v_cndmask_b32_e32 v128, v204, v128, vcc
	v_cmp_lt_i32_e32 vcc, 32, v221
	s_nop 1
	v_cndmask_b32_e32 v129, v204, v129, vcc
	v_cmp_lt_i32_e32 vcc, 33, v221
	s_nop 1
	v_cndmask_b32_e32 v126, v204, v126, vcc
	v_cmp_lt_i32_e32 vcc, 34, v221
	s_nop 1
	v_cndmask_b32_e32 v127, v204, v127, vcc
	v_cmp_lt_i32_e32 vcc, 47, v221
	s_nop 1
	v_cndmask_b32_e32 v124, v204, v124, vcc
	v_cmp_lt_i32_e32 vcc, 48, v221
	s_nop 1
	v_cndmask_b32_e32 v125, v204, v125, vcc
	v_cmp_lt_i32_e32 vcc, 49, v221
	s_nop 1
	v_cndmask_b32_e32 v122, v204, v122, vcc
	v_cmp_lt_i32_e32 vcc, 50, v221
	s_nop 1
	v_cndmask_b32_e32 v123, v204, v123, vcc

; #define LAS __attribute__((address_space(3)))
; template <int MODE> ...
;     ...
;     {
;         const LAS unsigned char* kb = lds + AL_KT + fr * KT_PITCH + fq * 16;
;     ...
;         bf16x8 kr[4]; kr[0] = KFRAG(0); kr[1] = KFRAG(1); kr[2] = KFRAG(2);
; #pragma unroll
;         for (int i = 0; i < 16; ++i) {
;             if (i + 3 < 16) kr[(i + 3) & 3] = KFRAG(i + 3);
;             __builtin_amdgcn_sched_barrier(0);
;             s[0][i & 3] = __builtin_amdgcn_mfma_f32_16x16x32_bf16(kr[i & 3], qf[0][i >> 2], s[0][i & 3], 0, 0, 0);
;             s[1][i & 3] = __builtin_amdgcn_mfma_f32_16x16x32_bf16(kr[i & 3], qf[1][i >> 2], s[1][i & 3], 0, 0, 0);
;             __builtin_amdgcn_sched_barrier(0);
;         }
;     ...
;     }
;     const float sk = slope2 * (float)KS;
;     float alpha[2] = {1.f, 1.f};
; #pragma unroll
;     for (int ci = 0; ci < 2; ++ci) {
;         const int base = tpos[ci] - kp0 - KS * (fq * 4);
;         const float bb = -slope2 * (float)base;
;         float mx = NEGB;
; #pragma unroll
;         for (int k4 = 0; k4 < 4; ++k4)
; #pragma unroll
;             for (int j = 0; j < 4; ++j) {
;                 s[ci][k4][j] = __builtin_fmaf(s[ci][k4][j], QSCALE2, __builtin_fmaf(sk, (float)(k4 * 16 + j), bb)); }
;         if (MASK) {
; #pragma unroll
;             for (int k4 = 0; k4 < 4; ++k4)
; #pragma unroll
;                 for (int j = 0; j < 4; ++j) { const int c = KS * (k4 * 16 + j); bool ok = c <= base; if (MODE == 3) ok = ok && (base - c < 512); s[ci][k4][j] = ok ? s[ci][k4][j] : 2.0f * NEGB; } }
.LBB0_3852:
	v_add3_u32 v164, s8, v210, v136
	ds_read_b128 v[116:119], v164 offset:8704
	ds_read_b128 v[120:123], v164 offset:13056
	ds_read_b128 v[124:127], v164 offset:4352
	ds_read_b128 v[128:131], v164
	s_cmp_eq_u32 s6, -7
	s_cselect_b64 s[0:1], -1, 0
	s_waitcnt lgkmcnt(0)
	v_mfma_f32_16x16x32_bf16 v[168:171], v[128:131], v[4:7], 0
	v_mfma_f32_16x16x32_bf16 v[128:131], v[128:131], v[20:23], 0
	ds_read_b128 v[172:175], v164 offset:64
	v_mfma_f32_16x16x32_bf16 v[176:179], v[124:127], v[4:7], 0
	v_mfma_f32_16x16x32_bf16 v[124:127], v[124:127], v[20:23], 0
	ds_read_b128 v[180:183], v164 offset:4416
	v_mfma_f32_16x16x32_bf16 v[186:189], v[116:119], v[4:7], 0
	v_mfma_f32_16x16x32_bf16 v[116:119], v[116:119], v[20:23], 0
	ds_read_b128 v[190:193], v164 offset:8768
	v_mfma_f32_16x16x32_bf16 v[216:219], v[120:123], v[4:7], 0
	v_mfma_f32_16x16x32_bf16 v[120:123], v[120:123], v[20:23], 0
	ds_read_b128 v[220:223], v164 offset:13120
	s_waitcnt lgkmcnt(3)
	v_mfma_f32_16x16x32_bf16 v[168:171], v[172:175], v[8:11], v[168:171]
	v_mfma_f32_16x16x32_bf16 v[128:131], v[172:175], v[24:27], v[128:131]
	ds_read_b128 v[172:175], v164 offset:128
	s_waitcnt lgkmcnt(3)
	v_mfma_f32_16x16x32_bf16 v[176:179], v[180:183], v[8:11], v[176:179]
	v_mfma_f32_16x16x32_bf16 v[124:127], v[180:183], v[24:27], v[124:127]
	ds_read_b128 v[180:183], v164 offset:4480
	s_waitcnt lgkmcnt(3)
	v_mfma_f32_16x16x32_bf16 v[116:119], v[190:193], v[24:27], v[116:119]
	v_mfma_f32_16x16x32_bf16 v[186:189], v[190:193], v[8:11], v[186:189]
	ds_read_b128 v[190:193], v164 offset:8832
	s_waitcnt lgkmcnt(3)
	v_mfma_f32_16x16x32_bf16 v[120:123], v[220:223], v[24:27], v[120:123]
	v_mfma_f32_16x16x32_bf16 v[216:219], v[220:223], v[8:11], v[216:219]
	ds_read_b128 v[220:223], v164 offset:13184
	s_waitcnt lgkmcnt(3)
	v_mfma_f32_16x16x32_bf16 v[168:171], v[172:175], v[12:15], v[168:171]
	v_mfma_f32_16x16x32_bf16 v[128:131], v[172:175], v[28:31], v[128:131]
	ds_read_b128 v[172:175], v164 offset:192
	s_waitcnt lgkmcnt(3)
	v_mfma_f32_16x16x32_bf16 v[176:179], v[180:183], v[12:15], v[176:179]
	v_mfma_f32_16x16x32_bf16 v[124:127], v[180:183], v[28:31], v[124:127]
	ds_read_b128 v[180:183], v164 offset:4544
	s_waitcnt lgkmcnt(3)
	v_mfma_f32_16x16x32_bf16 v[116:119], v[190:193], v[28:31], v[116:119]
	v_mfma_f32_16x16x32_bf16 v[186:189], v[190:193], v[12:15], v[186:189]
	ds_read_b128 v[190:193], v164 offset:8896
	s_waitcnt lgkmcnt(3)
	v_mfma_f32_16x16x32_bf16 v[216:219], v[220:223], v[12:15], v[216:219]
	v_mfma_f32_16x16x32_bf16 v[220:223], v[220:223], v[28:31], v[120:123]
	ds_read_b128 v[224:227], v164 offset:13248
	s_waitcnt lgkmcnt(3)
	v_mfma_f32_16x16x32_bf16 v[168:171], v[172:175], v[16:19], v[168:171]
	v_mfma_f32_16x16x32_bf16 v[128:131], v[172:175], v[32:35], v[128:131]
	s_waitcnt lgkmcnt(2)
	v_mfma_f32_16x16x32_bf16 v[172:175], v[180:183], v[16:19], v[176:179]
	v_mfma_f32_16x16x32_bf16 v[124:127], v[180:183], v[32:35], v[124:127]
	s_waitcnt lgkmcnt(1)
	v_mfma_f32_16x16x32_bf16 v[120:123], v[190:193], v[32:35], v[116:119]
	v_mfma_f32_16x16x32_bf16 v[186:189], v[190:193], v[16:19], v[186:189]
	s_waitcnt lgkmcnt(0)
	v_mfma_f32_16x16x32_bf16 v[116:119], v[224:227], v[32:35], v[220:223]
	v_mfma_f32_16x16x32_bf16 v[190:193], v[224:227], v[16:19], v[216:219]
	v_add_u32_e32 v182, -4, v1
	v_cvt_f32_i32_e32 v165, v182
	s_mov_b32 s10, 2.0
	s_mov_b32 s12, 0x3e0293ee
	s_mov_b32 s11, 0x40400000
	v_mul_f32_e64 v164, -v138, v165
	v_fma_f32 v176, 0, v138, v164
	v_fma_f32 v177, -v138, v165, v138
	v_fma_f32 v178, v168, s12, v176
	v_fma_f32 v179, v169, s12, v177
	v_fma_f32 v168, v138, s10, v164
	v_fma_f32 v169, v139, s11, v164
	s_mov_b32 s10, 0x41800000
	s_mov_b32 s11, 0x41880000
	v_fma_f32 v180, v170, s12, v168
	v_fma_f32 v181, v171, s12, v169
	v_fma_f32 v168, v138, s10, v164
	v_fma_f32 v169, v139, s11, v164
	s_mov_b32 s10, 0x41900000
	s_mov_b32 s11, 0x41980000
	v_fma_f32 v176, v172, s12, v168
	v_fma_f32 v177, v173, s12, v169
	v_fma_f32 v168, v138, s10, v164
	v_fma_f32 v169, v139, s11, v164
	s_mov_b32 s10, 0x42000000
	s_mov_b32 s11, 0x42040000
	v_fma_f32 v174, v174, s12, v168
	v_fma_f32 v175, v175, s12, v169
	v_fma_f32 v168, v138, s10, v164
	v_fma_f32 v169, v139, s11, v164
	s_mov_b32 s10, 0x42080000
	s_mov_b32 s11, 0x420c0000
	v_fma_f32 v172, v186, s12, v168
	v_fma_f32 v173, v187, s12, v169
	v_fma_f32 v168, v138, s10, v164
	v_fma_f32 v169, v139, s11, v164
	s_mov_b32 s10, 0x42400000
	s_mov_b32 s11, 0x42440000
	v_fma_f32 v170, v188, s12, v168
	v_fma_f32 v171, v189, s12, v169
	v_fma_f32 v168, v138, s10, v164
	v_fma_f32 v169, v139, s11, v164
	s_mov_b32 s10, 0x42480000
	s_mov_b32 s11, 0x424c0000
	v_fma_f32 v165, v139, s11, v164
	v_fma_f32 v164, v138, s10, v164
	v_fma_f32 v168, v190, s12, v168
	v_fma_f32 v169, v191, s12, v169
	v_fma_f32 v164, v192, s12, v164
	v_fma_f32 v165, v193, s12, v165
	s_and_b64 vcc, exec, s[0:1]
	s_cbranch_vccz .LBB0_3854
	s_movk_i32 s3, 0x200
	v_add_u32_e32 v183, -5, v1
	v_cmp_gt_u32_e32 vcc, s3, v182
	v_add_u32_e32 v185, -2, v182
	v_add_u32_e32 v186, -3, v182
	v_cndmask_b32_e32 v178, v204, v178, vcc
	v_cmp_gt_u32_e32 vcc, s3, v183
	v_add_u32_e32 v183, -16, v182
	v_subrev_u32_e32 v187, 19, v182
	v_cndmask_b32_e32 v179, v204, v179, vcc
	v_cmp_gt_u32_e32 vcc, s3, v185
	v_subrev_u32_e32 v185, 17, v182
	s_nop 0
	v_cndmask_b32_e32 v180, v204, v180, vcc
	v_cmp_gt_u32_e32 vcc, s3, v186
	v_subrev_u32_e32 v186, 18, v182
	s_nop 0
	v_cndmask_b32_e32 v181, v204, v181, vcc
	v_cmp_gt_u32_e32 vcc, s3, v183
	v_subrev_u32_e32 v183, 32, v182
	s_nop 0
	v_cndmask_b32_e32 v176, v204, v176, vcc
	v_cmp_gt_u32_e32 vcc, s3, v185
	v_subrev_u32_e32 v185, 33, v182
	s_nop 0
	v_cndmask_b32_e32 v177, v204, v177, vcc
	v_cmp_gt_u32_e32 vcc, s3, v186
	v_subrev_u32_e32 v186, 34, v182
	s_nop 0
	v_cndmask_b32_e32 v174, v204, v174, vcc
	v_cmp_gt_u32_e32 vcc, s3, v187
	v_subrev_u32_e32 v187, 35, v182
	s_nop 0
	v_cndmask_b32_e32 v175, v204, v175, vcc
	v_cmp_gt_u32_e32 vcc, s3, v183
	v_subrev_u32_e32 v183, 48, v182
	s_nop 0
	v_cndmask_b32_e32 v172, v204, v172, vcc
	v_cmp_gt_u32_e32 vcc, s3, v185
	v_subrev_u32_e32 v185, 49, v182
	s_nop 0
	v_cndmask_b32_e32 v173, v204, v173, vcc
	v_cmp_gt_u32_e32 vcc, s3, v186
	v_subrev_u32_e32 v186, 50, v182
	v_subrev_u32_e32 v182, 51, v182
	v_cndmask_b32_e32 v170, v204, v170, vcc
	v_cmp_gt_u32_e32 vcc, s3, v187
	s_nop 1
	v_cndmask_b32_e32 v171, v204, v171, vcc
	v_cmp_gt_u32_e32 vcc, s3, v183
	s_nop 1
	v_cndmask_b32_e32 v168, v204, v168, vcc
	v_cmp_gt_u32_e32 vcc, s3, v185
	s_nop 1
	v_cndmask_b32_e32 v169, v204, v169, vcc
	v_cmp_gt_u32_e32 vcc, s3, v186
	s_nop 1
	v_cndmask_b32_e32 v164, v204, v164, vcc
	v_cmp_gt_u32_e32 vcc, s3, v182
	s_nop 1
	v_cndmask_b32_e32 v165, v204, v165, vcc
; __device__ __forceinline__ float shx(float v, int lane, int o) { return __builtin_bit_cast(float, __builtin_amdgcn_ds_bpermute((lane ^ o) << 2, __builtin_bit_cast(int, v))); }
; template <int MODE> ...
;     ...
;     const float sk = slope2 * (float)KS;
;     float alpha[2] = {1.f, 1.f};
; #pragma unroll
;     for (int ci = 0; ci < 2; ++ci) {
;         const int base = tpos[ci] - kp0 - KS * (fq * 4);
;         const float bb = -slope2 * (float)base;
;         float mx = NEGB;
; #pragma unroll
;         for (int k4 = 0; k4 < 4; ++k4)
; #pragma unroll
;             for (int j = 0; j < 4; ++j) {
;                 s[ci][k4][j] = __builtin_fmaf(s[ci][k4][j], QSCALE2, __builtin_fmaf(sk, (float)(k4 * 16 + j), bb)); }
;         if (MASK) {
; #pragma unroll
;             for (int k4 = 0; k4 < 4; ++k4)
; #pragma unroll
;                 for (int j = 0; j < 4; ++j) { const int c = KS * (k4 * 16 + j); bool ok = c <= base; if (MODE == 3) ok = ok && (base - c < 512); s[ci][k4][j] = ok ? s[ci][k4][j] : 2.0f * NEGB; } }
; #pragma unroll
;         for (int k4 = 0; k4 < 4; ++k4)
; #pragma unroll
;             for (int j = 0; j < 4; ++j) mx = fmaxf(mx, s[ci][k4][j]);
;         if (MODE == 2) mx = selbit[ci] ? mx : NEGB;
;         if (MODE != 1) {
;             mx = fmaxf(mx, shx(mx, lane, 16)); mx = fmaxf(mx, shx(mx, lane, 32));
.LBB0_3854:
	s_mov_b32 s3, 0xf149f2ca
	v_max3_f32 v182, v178, s3, v179
	v_max3_f32 v182, v182, v180, v181
	v_max3_f32 v182, v182, v176, v177
	v_cvt_f32_i32_e32 v183, v1
	v_max3_f32 v182, v182, v174, v175
	v_max3_f32 v182, v182, v172, v173
	v_max3_f32 v182, v182, v170, v171
	v_max3_f32 v182, v182, v168, v169
	v_mul_f32_e64 v188, -v138, v183
	s_mov_b32 s10, 2.0
	v_max3_f32 v185, v182, v164, v165
	v_fma_f32 v183, -v138, v183, v138
	v_fma_f32 v182, 0, v138, v188
	s_mov_b32 s11, 0x40400000
	v_fma_f32 v182, v128, s12, v182
	v_fma_f32 v183, v129, s12, v183
	v_fma_f32 v128, v138, s10, v188
	v_fma_f32 v129, v139, s11, v188
	s_mov_b32 s10, 0x41800000
	s_mov_b32 s11, 0x41880000
	ds_bpermute_b32 v186, v137, v185
	v_fma_f32 v130, v130, s12, v128
	v_fma_f32 v131, v131, s12, v129
	v_fma_f32 v128, v138, s10, v188
	v_fma_f32 v129, v139, s11, v188
	s_mov_b32 s10, 0x41900000
	s_mov_b32 s11, 0x41980000
	v_fma_f32 v128, v124, s12, v128
	v_fma_f32 v129, v125, s12, v129
	v_fma_f32 v124, v138, s10, v188
	v_fma_f32 v125, v139, s11, v188
	s_mov_b32 s10, 0x42000000
	s_mov_b32 s11, 0x42040000
	v_fma_f32 v126, v126, s12, v124
	v_fma_f32 v127, v127, s12, v125
	v_fma_f32 v124, v138, s10, v188
	v_fma_f32 v125, v139, s11, v188
	s_mov_b32 s10, 0x42080000
	s_waitcnt lgkmcnt(0)
	v_max_f32_e32 v186, v186, v186
	s_mov_b32 s11, 0x420c0000
	v_max_f32_e32 v185, v185, v186
	v_fma_f32 v124, v120, s12, v124
	v_fma_f32 v125, v121, s12, v125
	v_fma_f32 v120, v138, s10, v188
	v_fma_f32 v121, v139, s11, v188
	s_mov_b32 s10, 0x42400000
	ds_bpermute_b32 v186, v207, v185
	s_mov_b32 s11, 0x42440000
	v_fma_f32 v122, v122, s12, v120
	v_fma_f32 v123, v123, s12, v121
	v_fma_f32 v120, v138, s10, v188
	v_fma_f32 v121, v139, s11, v188
	s_mov_b32 s10, 0x42480000
	s_mov_b32 s11, 0x424c0000
	v_fma_f32 v120, v116, s12, v120
	v_fma_f32 v121, v117, s12, v121
	v_fma_f32 v116, v138, s10, v188
	v_fma_f32 v117, v139, s11, v188
	s_andn2_b64 vcc, exec, s[0:1]
	v_fma_f32 v118, v118, s12, v116
	v_fma_f32 v119, v119, s12, v117
	s_cbranch_vccnz .LBB0_3856
	s_movk_i32 s0, 0x200
	v_add_u32_e32 v116, -1, v1
	v_cmp_gt_u32_e32 vcc, s0, v1
	v_add_u32_e32 v117, -2, v1
	v_add_u32_e32 v187, -3, v1
	v_cndmask_b32_e32 v182, v204, v182, vcc
	v_cmp_gt_u32_e32 vcc, s0, v116
	v_add_u32_e32 v116, -16, v1
	v_subrev_u32_e32 v188, 19, v1
	v_cndmask_b32_e32 v183, v204, v183, vcc
	v_cmp_gt_u32_e32 vcc, s0, v117
	v_subrev_u32_e32 v117, 17, v1
	s_nop 0
	v_cndmask_b32_e32 v130, v204, v130, vcc
	v_cmp_gt_u32_e32 vcc, s0, v187
	v_subrev_u32_e32 v187, 18, v1
	s_nop 0
	v_cndmask_b32_e32 v131, v204, v131, vcc
	v_cmp_gt_u32_e32 vcc, s0, v116
	v_subrev_u32_e32 v116, 32, v1
	s_nop 0
	v_cndmask_b32_e32 v128, v204, v128, vcc
	v_cmp_gt_u32_e32 vcc, s0, v117
	v_subrev_u32_e32 v117, 33, v1
	s_nop 0
	v_cndmask_b32_e32 v129, v204, v129, vcc
	v_cmp_gt_u32_e32 vcc, s0, v187
	v_subrev_u32_e32 v187, 34, v1
	s_nop 0
	v_cndmask_b32_e32 v126, v204, v126, vcc
	v_cmp_gt_u32_e32 vcc, s0, v188
	v_subrev_u32_e32 v188, 35, v1
	s_nop 0
	v_cndmask_b32_e32 v127, v204, v127, vcc
	v_cmp_gt_u32_e32 vcc, s0, v116
	v_subrev_u32_e32 v116, 48, v1
	s_nop 0
	v_cndmask_b32_e32 v124, v204, v124, vcc
	v_cmp_gt_u32_e32 vcc, s0, v117
	v_subrev_u32_e32 v117, 49, v1
	s_nop 0
	v_cndmask_b32_e32 v125, v204, v125, vcc
	v_cmp_gt_u32_e32 vcc, s0, v187
	v_subrev_u32_e32 v187, 50, v1
	s_nop 0
	v_cndmask_b32_e32 v122, v204, v122, vcc
	v_cmp_gt_u32_e32 vcc, s0, v188
	v_subrev_u32_e32 v188, 51, v1
	s_nop 0
	v_cndmask_b32_e32 v123, v204, v123, vcc
	v_cmp_gt_u32_e32 vcc, s0, v116
	s_nop 1
	v_cndmask_b32_e32 v120, v204, v120, vcc
	v_cmp_gt_u32_e32 vcc, s0, v117
	s_nop 1
	v_cndmask_b32_e32 v121, v204, v121, vcc
	v_cmp_gt_u32_e32 vcc, s0, v187
	s_nop 1
	v_cndmask_b32_e32 v118, v204, v118, vcc
	v_cmp_gt_u32_e32 vcc, s0, v188
	s_nop 1
	v_cndmask_b32_e32 v119, v204, v119, vcc

; __device__ __forceinline__ unsigned pk2(float lo, float hi) { unsigned r; asm volatile("v_cvt_pk_bf16_f32 %0, %1, %2" : "=v"(r) : "v"(lo), "v"(hi)); return r; }
; __device__ __forceinline__ float shx(float v, int lane, int o) { return __builtin_bit_cast(float, __builtin_amdgcn_ds_bpermute((lane ^ o) << 2, __builtin_bit_cast(int, v))); }
; __device__ __forceinline__ void nsa_item(LAS unsigned char* lds, int b, int g, int tq, const bf16_t* Q, const bf16_t* KS, const bf16_t* VST, const bf16_t* KW, const bf16_t* VWT,
;                                          const bf16_t* KCMP, const bf16_t* VCMPT, const float* GL, bf16_t* YB) {
;     ...
;     for (int ci = 0; ci < 2; ++ci) { float lt = l[ci]; lt += shx(lt, lane, 16); lt += shx(lt, lane, 32); const float gwv = GL[((size_t)(b * SEQ + tpos[ci])) * 48 + 32 + head]; const float sc = lt > 0.f ? gwv / lt : 0.f;
;         bf16_t* op = YB + ((size_t)(b * SEQ + tpos[ci])) * DM + head * 128 + fq * 4;
; #pragma unroll
;         for (int dt = 0; dt < 8; ++dt) { const f32x4 o = O[ci][dt] * sc; const u32x2 pv = *(const u32x2*)(op + dt * 16); u32x2 w; w.x = pk2(bflo(pv.x) + o[0], bfhi(pv.x) + o[1]); w.y = pk2(bflo(pv.y) + o[2], bfhi(pv.y) + o[3]); *(u32x2*)(op + dt * 16) = w; } }
.LBB0_3863:
	s_or_b64 exec, exec, s[0:1]
	global_load_dwordx2 v[12:13], v[162:163], off
	v_pk_mul_f32 v[10:11], v[112:113], v[6:7] op_sel_hi:[1,0]
	v_pk_mul_f32 v[8:9], v[114:115], v[6:7] op_sel_hi:[1,0]
	s_waitcnt vmcnt(0)
	v_lshlrev_b32_e32 v1, 16, v12
	v_and_b32_e32 v3, 0xffff0000, v12
	v_add_f32_e32 v1, v10, v1
	v_add_f32_e32 v3, v11, v3
	v_cvt_pk_bf16_f32 v10, v1, v3
	v_lshlrev_b32_e32 v1, 16, v13
	v_and_b32_e32 v3, 0xffff0000, v13
	v_add_f32_e32 v1, v8, v1
	v_add_f32_e32 v3, v9, v3
	v_cvt_pk_bf16_f32 v11, v1, v3
	global_load_dwordx2 v[12:13], v[162:163], off offset:32
	v_pk_mul_f32 v[8:9], v[110:111], v[6:7] op_sel_hi:[1,0]
	global_store_dwordx2 v[162:163], v[10:11], off
	v_pk_mul_f32 v[10:11], v[108:109], v[6:7] op_sel_hi:[1,0]
	s_waitcnt vmcnt(1)
	v_lshlrev_b32_e32 v1, 16, v12
	v_and_b32_e32 v3, 0xffff0000, v12
	v_add_f32_e32 v1, v10, v1
	v_add_f32_e32 v3, v11, v3
	v_cvt_pk_bf16_f32 v10, v1, v3
	v_lshlrev_b32_e32 v1, 16, v13
	v_and_b32_e32 v3, 0xffff0000, v13
	v_add_f32_e32 v1, v8, v1
	v_add_f32_e32 v3, v9, v3
	v_cvt_pk_bf16_f32 v11, v1, v3
	global_load_dwordx2 v[12:13], v[162:163], off offset:64
	v_pk_mul_f32 v[8:9], v[106:107], v[6:7] op_sel_hi:[1,0]
	global_store_dwordx2 v[162:163], v[10:11], off offset:32
	v_pk_mul_f32 v[10:11], v[104:105], v[6:7] op_sel_hi:[1,0]
	s_waitcnt vmcnt(1)
	v_lshlrev_b32_e32 v1, 16, v12
	v_and_b32_e32 v3, 0xffff0000, v12
	v_add_f32_e32 v1, v10, v1
	v_add_f32_e32 v3, v11, v3
	v_cvt_pk_bf16_f32 v10, v1, v3
	v_lshlrev_b32_e32 v1, 16, v13
	v_and_b32_e32 v3, 0xffff0000, v13
	v_add_f32_e32 v1, v8, v1
	v_add_f32_e32 v3, v9, v3
	v_cvt_pk_bf16_f32 v11, v1, v3
	global_load_dwordx2 v[12:13], v[162:163], off offset:96
	v_pk_mul_f32 v[8:9], v[86:87], v[6:7] op_sel_hi:[1,0]
	global_store_dwordx2 v[162:163], v[10:11], off offset:64
	v_pk_mul_f32 v[10:11], v[84:85], v[6:7] op_sel_hi:[1,0]
	s_waitcnt vmcnt(1)
	v_lshlrev_b32_e32 v1, 16, v12
	v_and_b32_e32 v3, 0xffff0000, v12
	v_add_f32_e32 v1, v10, v1
	v_add_f32_e32 v3, v11, v3
	v_cvt_pk_bf16_f32 v10, v1, v3
	v_lshlrev_b32_e32 v1, 16, v13
	v_and_b32_e32 v3, 0xffff0000, v13
	v_add_f32_e32 v1, v8, v1
	v_add_f32_e32 v3, v9, v3
	v_cvt_pk_bf16_f32 v11, v1, v3
	global_load_dwordx2 v[12:13], v[162:163], off offset:128
	v_pk_mul_f32 v[8:9], v[82:83], v[6:7] op_sel_hi:[1,0]
	global_store_dwordx2 v[162:163], v[10:11], off offset:96
	v_pk_mul_f32 v[10:11], v[80:81], v[6:7] op_sel_hi:[1,0]
	s_waitcnt vmcnt(1)
	v_lshlrev_b32_e32 v1, 16, v12
	v_and_b32_e32 v3, 0xffff0000, v12
	v_add_f32_e32 v1, v10, v1
	v_add_f32_e32 v3, v11, v3
	v_cvt_pk_bf16_f32 v10, v1, v3
	v_lshlrev_b32_e32 v1, 16, v13
	v_and_b32_e32 v3, 0xffff0000, v13
	v_add_f32_e32 v1, v8, v1
	v_add_f32_e32 v3, v9, v3
	v_cvt_pk_bf16_f32 v11, v1, v3
	global_load_dwordx2 v[12:13], v[162:163], off offset:160
	v_pk_mul_f32 v[8:9], v[78:79], v[6:7] op_sel_hi:[1,0]
	global_store_dwordx2 v[162:163], v[10:11], off offset:128
	v_pk_mul_f32 v[10:11], v[76:77], v[6:7] op_sel_hi:[1,0]
	s_waitcnt vmcnt(1)
	v_lshlrev_b32_e32 v1, 16, v12
	v_and_b32_e32 v3, 0xffff0000, v12
	v_add_f32_e32 v1, v10, v1
	v_add_f32_e32 v3, v11, v3
	v_cvt_pk_bf16_f32 v10, v1, v3
	v_lshlrev_b32_e32 v1, 16, v13
	v_and_b32_e32 v3, 0xffff0000, v13
	v_add_f32_e32 v1, v8, v1
	v_add_f32_e32 v3, v9, v3
	v_cvt_pk_bf16_f32 v11, v1, v3
	global_load_dwordx2 v[12:13], v[162:163], off offset:192
	v_pk_mul_f32 v[8:9], v[74:75], v[6:7] op_sel_hi:[1,0]
	global_store_dwordx2 v[162:163], v[10:11], off offset:160
	v_pk_mul_f32 v[10:11], v[72:73], v[6:7] op_sel_hi:[1,0]
	s_waitcnt vmcnt(1)
	v_lshlrev_b32_e32 v1, 16, v12
	v_and_b32_e32 v3, 0xffff0000, v12
	v_add_f32_e32 v1, v10, v1
	v_add_f32_e32 v3, v11, v3
	v_cvt_pk_bf16_f32 v10, v1, v3
	v_lshlrev_b32_e32 v1, 16, v13
	v_and_b32_e32 v3, 0xffff0000, v13
	v_add_f32_e32 v1, v8, v1
	v_add_f32_e32 v3, v9, v3
	v_cvt_pk_bf16_f32 v11, v1, v3
	global_store_dwordx2 v[162:163], v[10:11], off offset:192
	global_load_dwordx2 v[10:11], v[162:163], off offset:224
	v_pk_mul_f32 v[8:9], v[70:71], v[6:7] op_sel_hi:[1,0]
	v_pk_mul_f32 v[6:7], v[68:69], v[6:7] op_sel_hi:[1,0]
	s_waitcnt vmcnt(0)
	v_lshlrev_b32_e32 v1, 16, v10
	v_add_f32_e32 v1, v6, v1
	v_and_b32_e32 v3, 0xffff0000, v10
	v_add_f32_e32 v3, v7, v3
	v_cvt_pk_bf16_f32 v6, v1, v3
	v_lshlrev_b32_e32 v1, 16, v11
	v_add_f32_e32 v1, v8, v1
	v_and_b32_e32 v3, 0xffff0000, v11
	v_add_f32_e32 v3, v9, v3
	v_cvt_pk_bf16_f32 v7, v1, v3
	ds_bpermute_b32 v1, v137, v167
	global_store_dwordx2 v[162:163], v[6:7], off offset:224
	s_waitcnt lgkmcnt(0)
	v_add_f32_e32 v1, v167, v1
	ds_bpermute_b32 v3, v207, v1
	s_waitcnt lgkmcnt(0)
	v_add_f32_e32 v1, v1, v3
	v_cmp_lt_f32_e32 vcc, 0, v1
	s_and_saveexec_b64 s[0:1], vcc
	s_cbranch_execz .LBB0_3776
; __device__ __forceinline__ float shx(float v, int lane, int o) { return __builtin_bit_cast(float, __builtin_amdgcn_ds_bpermute((lane ^ o) << 2, __builtin_bit_cast(int, v))); }
; __device__ __forceinline__ void nsa_item(LAS unsigned char* lds, int b, int g, int tq, const bf16_t* Q, const bf16_t* KS, const bf16_t* VST, const bf16_t* KW, const bf16_t* VWT,
;                                          const bf16_t* KCMP, const bf16_t* VCMPT, const float* GL, bf16_t* YB) {
;     ...
;     for (int ci = 0; ci < 2; ++ci) { float lt = l[ci]; lt += shx(lt, lane, 16); lt += shx(lt, lane, 32); const float gwv = GL[((size_t)(b * SEQ + tpos[ci])) * 48 + 32 + head]; const float sc = lt > 0.f ? gwv / lt : 0.f;
	v_mov_b32_e32 v3, v0
	v_lshl_add_u64 v[2:3], v[132:133], 0, v[2:3]
	global_load_dword v2, v[2:3], off offset:128
	s_waitcnt vmcnt(0)
	v_div_scale_f32 v3, s[2:3], v1, v1, v2
	v_rcp_f32_e32 v4, v3
	v_div_scale_f32 v5, vcc, v2, v1, v2
	v_fma_f32 v6, -v3, v4, 1.0
	v_fmac_f32_e32 v4, v6, v4
	v_mul_f32_e32 v6, v5, v4
	v_fma_f32 v7, -v3, v6, v5
	v_fmac_f32_e32 v6, v7, v4
	v_fma_f32 v3, -v3, v6, v5
	v_div_fmas_f32 v3, v3, v4, v6
	v_div_fixup_f32 v4, v3, v1, v2
	s_branch .LBB0_3776
	s_nop 0
	s_nop 0
	s_nop 0
	s_nop 0
	s_nop 0
	s_nop 0
	s_nop 0
	s_nop 0
	s_nop 0
	s_nop 0
	s_nop 0
	s_nop 0
	s_nop 0
	s_nop 0
	s_nop 0
	s_nop 0
	s_nop 0
	s_nop 0
	s_nop 0
	s_nop 0
	s_nop 0
	s_nop 0
	s_nop 0
	s_nop 0
	s_nop 0
	s_nop 0
	s_nop 0
	s_nop 0
	s_nop 0
	s_nop 0
	s_nop 0
	s_nop 0
	s_nop 0
	s_nop 0
	s_nop 0
	s_nop 0
	s_nop 0
	s_nop 0
	s_nop 0
	s_nop 0
	s_nop 0
	s_nop 0
	s_nop 0
	s_nop 0
	s_nop 0
	s_nop 0
	s_nop 0
	s_nop 0
	s_nop 0
	s_nop 0
	s_nop 0
	s_nop 0
	s_nop 0
	s_nop 0
	s_nop 0
	s_nop 0
	s_nop 0
	s_nop 0
	s_nop 0
	s_nop 0
	s_nop 0
	s_nop 0
	s_nop 0
	s_nop 0
	s_nop 0
	s_nop 0
	s_nop 0
	s_nop 0
	s_nop 0
	s_nop 0
	s_nop 0
	s_nop 0
	s_nop 0
	s_nop 0
	s_nop 0
	s_nop 0
	s_nop 0
	s_nop 0
	s_nop 0
	s_nop 0
	s_nop 0
	s_nop 0
	s_nop 0
	s_nop 0
	s_nop 0
	s_nop 0
	s_nop 0
	s_nop 0
	s_nop 0
	s_nop 0
	s_nop 0
	s_nop 0
	s_nop 0
	s_nop 0
	s_nop 0
	s_nop 0
	s_nop 0
	s_nop 0
	s_nop 0
	s_nop 0
	s_nop 0
	s_nop 0
	s_nop 0
	s_nop 0
	s_nop 0
	s_nop 0
	s_nop 0
	s_nop 0
	s_nop 0
	s_nop 0
	s_nop 0
	s_nop 0
	s_nop 0
	s_nop 0
	s_nop 0
	s_nop 0
	s_nop 0
	s_nop 0
	s_nop 0
	s_nop 0
	s_nop 0
	s_nop 0
	s_nop 0
	s_nop 0
	s_nop 0
	s_nop 0
	s_nop 0
	s_nop 0
	s_nop 0
	s_nop 0
	s_nop 0
	s_nop 0
	s_nop 0
	s_nop 0
	s_nop 0
	s_nop 0
	s_nop 0
	s_nop 0
	s_nop 0
	s_nop 0
	s_nop 0
	s_nop 0
	s_nop 0
	s_nop 0
	s_nop 0
	s_nop 0
	s_nop 0
	s_nop 0
	s_nop 0
	s_nop 0
	s_nop 0
	s_nop 0
	s_nop 0
	s_nop 0
	s_nop 0
	s_nop 0
	s_nop 0
	s_nop 0
	s_nop 0
	s_nop 0
	s_nop 0
	s_nop 0
	s_nop 0
	s_nop 0
	s_nop 0
	s_nop 0
	s_nop 0
	s_nop 0
	s_nop 0
	s_nop 0
	s_nop 0
	s_nop 0
	s_nop 0
	s_nop 0
	s_nop 0
	s_nop 0
	s_nop 0
	s_nop 0
	s_nop 0
	s_nop 0
	s_nop 0
	s_nop 0
	s_nop 0
	s_nop 0
	s_nop 0
	s_nop 0
	s_nop 0
	s_nop 0
	s_nop 0
	s_nop 0
	s_nop 0
	s_nop 0
	s_nop 0
	s_nop 0
	s_nop 0
	s_nop 0
	s_nop 0
	s_nop 0
	s_nop 0
	s_nop 0
	s_nop 0
	s_nop 0
	s_nop 0
	s_nop 0
	s_nop 0
	s_nop 0
	s_nop 0
	s_nop 0
	s_nop 0
	s_nop 0
	s_nop 0
	s_nop 0
	s_nop 0
	s_nop 0
	s_nop 0
	s_nop 0
	s_nop 0
	s_nop 0
	s_nop 0
	s_nop 0
	s_nop 0
	s_nop 0
	s_nop 0
	s_nop 0
	s_nop 0
	s_nop 0
	s_nop 0
	s_nop 0
	s_nop 0
	s_nop 0
	s_nop 0
	s_nop 0
	s_nop 0
	s_nop 0
	s_nop 0
	s_nop 0
	s_nop 0
	s_nop 0
	s_nop 0
	s_nop 0
	s_nop 0
	s_nop 0
	s_nop 0
	s_nop 0
	s_nop 0
	s_nop 0
	s_nop 0
	s_nop 0
	s_nop 0
	s_nop 0
	s_nop 0
	s_nop 0
	s_nop 0
	s_nop 0
	s_nop 0
	s_nop 0
	s_nop 0
	s_nop 0
	s_nop 0
	s_nop 0
	s_nop 0
	s_nop 0
	s_nop 0
	s_nop 0
	s_nop 0
	s_nop 0
	s_nop 0
	s_nop 0
	s_nop 0
	s_nop 0
	s_nop 0
	s_nop 0
